# attention PV: all eight transposed V reads issued before the four PV MFMAs with counted lgkmcnt (was read-wait-mfma x4)
# speedup vs baseline: 1.0295x; 1.0028x over previous
.LBB0_619:
	v_add_f32_e32 v21, 0, v21
	v_add_f32_e32 v21, v22, v21
	v_add_f32_e32 v21, v23, v21
	v_add_f32_e32 v21, v24, v21
	v_add_f32_e32 v21, v25, v21
	v_add_f32_e32 v21, v26, v21
	v_add_f32_e32 v21, v27, v21
	v_add_f32_e32 v24, v28, v21
	v_fmac_f32_e32 v24, v112, v20
	ds_read_b64_tr_b16 v[114:115], v106 offset:16384
	ds_read_b64_tr_b16 v[116:117], v107 offset:16384
	ds_read_b64_tr_b16 v[118:119], v106 offset:16416
	ds_read_b64_tr_b16 v[120:121], v107 offset:16416
	ds_read_b64_tr_b16 v[122:123], v106 offset:16448
	ds_read_b64_tr_b16 v[124:125], v107 offset:16448
	ds_read_b64_tr_b16 v[126:127], v106 offset:16480
	ds_read_b64_tr_b16 v[128:129], v107 offset:16480
	s_setprio 1
	s_waitcnt lgkmcnt(6)
	v_mfma_f32_16x16x32_bf16 v[8:11], v[114:117], v[16:19], v[8:11]
	s_waitcnt lgkmcnt(4)
	v_mfma_f32_16x16x32_bf16 v[4:7], v[118:121], v[16:19], v[4:7]
	s_waitcnt lgkmcnt(2)
	v_mfma_f32_16x16x32_bf16 v[0:3], v[122:125], v[16:19], v[0:3]
	s_waitcnt lgkmcnt(0)
	v_mfma_f32_16x16x32_bf16 v[12:15], v[126:129], v[16:19], v[12:15]
	s_setprio 0
	v_and_b32_e32 v17, 64, v234
	v_xor_b32_e32 v16, 16, v234
	v_add_u32_e32 v17, 64, v17
	v_cmp_lt_i32_e32 vcc, v16, v17
	v_xor_b32_e32 v18, 32, v234
	s_add_i32 s0, s0, s82
	v_cndmask_b32_e32 v16, v234, v16, vcc
	v_lshlrev_b32_e32 v16, 2, v16
	ds_bpermute_b32 v16, v16, v24
	v_cmp_lt_i32_e32 vcc, v18, v17
	s_cmpk_gt_i32 s0, 0x2fff
	s_waitcnt lgkmcnt(0)
	v_add_f32_e32 v16, v24, v16
	v_cndmask_b32_e32 v17, v234, v18, vcc
	v_lshlrev_b32_e32 v17, 2, v17
	ds_bpermute_b32 v17, v17, v16
	s_waitcnt lgkmcnt(0)
	v_add_f32_e32 v16, v16, v17
	v_div_scale_f32 v17, s[6:7], v16, v16, 1.0
	v_rcp_f32_e32 v18, v17
	s_nop 0
	v_fma_f32 v19, -v17, v18, 1.0
	v_fmac_f32_e32 v18, v19, v18
	v_div_scale_f32 v19, vcc, 1.0, v16, 1.0
	v_mul_f32_e32 v20, v19, v18
	v_fma_f32 v21, -v17, v20, v19
	v_fmac_f32_e32 v20, v21, v18
	v_fma_f32 v17, -v17, v20, v19
	v_div_fmas_f32 v17, v17, v18, v20
	v_lshlrev_b64 v[18:19], 11, v[50:51]
	v_lshl_add_u64 v[18:19], s[24:25], 0, v[18:19]
	v_div_fixup_f32 v16, v17, v16, 1.0
	v_lshl_add_u64 v[18:19], s[2:3], 1, v[18:19]
	v_lshl_add_u64 v[18:19], v[100:101], 1, v[18:19]
	v_pk_mul_f32 v[8:9], v[8:9], v[16:17] op_sel_hi:[1,0]
	v_pk_mul_f32 v[4:5], v[4:5], v[16:17] op_sel_hi:[1,0]
	v_pk_mul_f32 v[2:3], v[2:3], v[16:17] op_sel_hi:[1,0]
	v_pk_mul_f32 v[0:1], v[0:1], v[16:17] op_sel_hi:[1,0]
	v_pk_mul_f32 v[10:11], v[10:11], v[16:17] op_sel_hi:[1,0]
	v_cvt_pk_bf16_f32 v8, v8, v9
	v_pk_mul_f32 v[6:7], v[6:7], v[16:17] op_sel_hi:[1,0]
	v_cvt_pk_bf16_f32 v9, v10, v11
	global_store_dwordx2 v[18:19], v[8:9], off
	v_cvt_pk_bf16_f32 v4, v4, v5
	v_cvt_pk_bf16_f32 v5, v6, v7
	global_store_dwordx2 v[18:19], v[4:5], off offset:32
	v_cvt_pk_bf16_f32 v0, v0, v1
	v_cvt_pk_bf16_f32 v1, v2, v3
	v_pk_mul_f32 v[2:3], v[12:13], v[16:17] op_sel_hi:[1,0]
	global_store_dwordx2 v[18:19], v[0:1], off offset:64
	v_pk_mul_f32 v[0:1], v[14:15], v[16:17] op_sel_hi:[1,0]
	v_cvt_pk_bf16_f32 v2, v2, v3
	s_nop 0
	v_cvt_pk_bf16_f32 v3, v0, v1
	global_store_dwordx2 v[18:19], v[2:3], off offset:96
	s_cbranch_scc1 .LBB0_641

.LBB0_634:
	v_add_f32_e32 v12, 0, v69
	v_add_f32_e32 v12, v70, v12
	v_add_f32_e32 v12, v71, v12
	v_add_f32_e32 v12, v72, v12
	v_add_f32_e32 v12, v73, v12
	v_add_f32_e32 v12, v74, v12
	v_add_f32_e32 v12, v75, v12
	v_add_f32_e32 v112, v76, v12
	ds_read_b64_tr_b16 v[114:115], v106 offset:16384
	ds_read_b64_tr_b16 v[116:117], v107 offset:16384
	ds_read_b64_tr_b16 v[118:119], v106 offset:16416
	ds_read_b64_tr_b16 v[120:121], v107 offset:16416
	ds_read_b64_tr_b16 v[122:123], v106 offset:16448
	ds_read_b64_tr_b16 v[124:125], v107 offset:16448
	ds_read_b64_tr_b16 v[126:127], v106 offset:16480
	ds_read_b64_tr_b16 v[128:129], v107 offset:16480
	v_fmac_f32_e32 v112, v111, v68
	s_setprio 1
	s_waitcnt lgkmcnt(6)
	v_mfma_f32_16x16x32_bf16 v[8:11], v[114:117], v[64:67], v[8:11]
	s_waitcnt lgkmcnt(4)
	v_mfma_f32_16x16x32_bf16 v[4:7], v[118:121], v[64:67], v[4:7]
	s_waitcnt lgkmcnt(2)
	v_mfma_f32_16x16x32_bf16 v[0:3], v[122:125], v[64:67], v[0:3]
	s_waitcnt lgkmcnt(0)
	v_mfma_f32_16x16x32_bf16 v[12:15], v[126:129], v[64:67], v[32:35]
	s_setprio 0
	s_add_i32 s16, s16, 1
	s_cmp_eq_u32 s16, 11
	s_cbranch_scc1 .LBB0_636
	s_waitcnt vmcnt(4)
	v_mov_b64_e32 v[66:67], v[30:31]
	v_mov_b64_e32 v[70:71], v[26:27]
	v_mov_b64_e32 v[74:75], v[42:43]
	v_mov_b64_e32 v[78:79], v[38:39]
	s_waitcnt vmcnt(0)
	v_mov_b64_e32 v[90:91], v[62:63]
	v_mov_b64_e32 v[94:95], v[58:59]
	v_mov_b64_e32 v[82:83], v[54:55]
	v_mov_b64_e32 v[86:87], v[46:47]
	v_mov_b64_e32 v[64:65], v[28:29]
	v_mov_b64_e32 v[68:69], v[24:25]
	v_mov_b64_e32 v[72:73], v[40:41]
	v_mov_b64_e32 v[76:77], v[36:37]
	v_mov_b64_e32 v[88:89], v[60:61]
	v_mov_b64_e32 v[92:93], v[56:57]
	v_mov_b64_e32 v[80:81], v[52:53]
	v_mov_b64_e32 v[84:85], v[44:45]
	v_mov_b32_e32 v111, v112
	s_mov_b32 s18, s17
	v_mov_b32_e32 v32, v12
	v_mov_b32_e32 v33, v13
	v_mov_b32_e32 v34, v14
	v_mov_b32_e32 v35, v15
	s_branch .LBB0_621
